# K-loops: s_setprio 1 moved in front of the barrier that releases the MFMA segment (on top of merged priority windows)
# baseline (speedup 1.0000x reference)
; #define PG8_STAGE(bufoff, gbase, voff) do { _Pragma("unroll") for (int _i = 0; _i < 2; ++_i) \
;         __builtin_amdgcn_global_load_lds((const unsigned*)((const char*)(gbase) + (voff)[_i]), (PG8_LAS unsigned*)(lds + (bufoff) + ldsw + _i * 8192), 16, 0, 0); } while (0)
; #define PG8_LDA(dst, b, h) do { _Pragma("unroll") for (int m = 0; m < 4; ++m) _Pragma("unroll") for (int k = 0; k < 2; ++k) dst[m][k] = *(const PG8_LAS bf16x8*)(lds + PG8_SA(b, h) + aoff + m * 2048 + k * 1024); } while (0)
; #define PG8_LDB(dst, b, h) do { _Pragma("unroll") for (int n = 0; n < 2; ++n) _Pragma("unroll") for (int k = 0; k < 2; ++k) dst[n][k] = *(const PG8_LAS bf16x8*)(lds + PG8_SB(b, h) + boff + n * 2048 + k * 1024); } while (0)
; #define PG8_MMA(ai, bj, At, Bt) do { __builtin_amdgcn_s_setprio(1); _Pragma("unroll") for (int m = 0; m < 4; ++m) _Pragma("unroll") for (int n = 0; n < 2; ++n) _Pragma("unroll") for (int k = 0; k < 2; ++k) \
;         acc[ai][bj][m][n] = __builtin_amdgcn_mfma_f32_16x16x32_bf16(Bt[n][k], At[m][k], acc[ai][bj][m][n], 0, 0, 0); __builtin_amdgcn_s_setprio(0); } while (0)
; #define PG8_WAIT_V(n) asm volatile("s_waitcnt vmcnt(" #n ")" ::: "memory")
; #define PG8_WAIT_L(n) asm volatile("s_waitcnt lgkmcnt(" #n ")" ::: "memory")
; #define PG8_BAR __builtin_amdgcn_s_barrier()
; #define PG8_SCHED __builtin_amdgcn_sched_barrier(0)
; template <class Epi, class Sched, bool ALIGN_EPI = false, bool SP2 = false>
; __device__ __forceinline__ void gemm_phase(PG8_LAS unsigned char* lds, const Gemm g, const Sched& S, const Epi& E, int tid_in) {
;     ...
;         for (int t = 0; t < nt; t += 2) {
;             const bool last = (t == nt - 2);
;             const char* a1 = cA + (size_t)(t + 1) * kstep;
;             const char* a2 = last ? nA : cA + (size_t)(t + 2) * kstep; const char* b2 = last ? nB : cB + (size_t)(t + 2) * kstep;
;             const char* a3 = a2 + kstep; const char* b3 = b2 + kstep;
;             if (last && has_next) S.a_ready(nxt);
;             if constexpr (SP2) {
;             PG8_LDB(B0, 0, 0); PG8_LDB(B1, 0, 1); PG8_SCHED; PG8_LDA(At, 0, 0); PG8_STAGE(PG8_SA(1, 1), a1 + hstep, voffA);
;             PG8_WAIT_V(8); PG8_WAIT_L(0); PG8_BAR; PG8_MMA(0, 0, At, B0); PG8_MMA(0, 1, At, B1); PG8_BAR; PG8_SCHED;
;             PG8_LDA(At, 0, 1); PG8_STAGE(PG8_SB(0, 0), b2, voffB); PG8_STAGE(PG8_SB(0, 1), b2 + hstep, voffB); PG8_STAGE(PG8_SA(0, 0), a2, voffA);
.LBB0_219:
	s_add_u32 s0, s24, 0xfffc0080
	s_addc_u32 s1, s25, -1
	s_add_i32 s2, 0, 0x10000
	s_cmp_eq_u32 s55, 12
	s_cselect_b32 s29, s7, s1
	s_cselect_b32 s28, s9, s0
	s_cselect_b32 s27, s17, s54
	s_cselect_b32 s26, s19, s53
	s_add_i32 s3, 0, 0x14000
	v_add_u32_e32 v140, s2, v168
	v_add_u32_e32 v174, s3, v168
	ds_read_b128 v[128:131], v140
	ds_read_b128 v[132:135], v140 offset:1024
	ds_read_b128 v[136:139], v140 offset:2048
	ds_read_b128 v[140:143], v140 offset:3072
	ds_read_b128 v[158:161], v174
	ds_read_b128 v[162:165], v174 offset:1024
	ds_read_b128 v[170:173], v174 offset:2048
	ds_read_b128 v[174:177], v174 offset:3072
	v_lshl_add_u64 v[210:211], s[24:25], 0, v[154:155]
	s_add_i32 m0, s41, 0xc000
	ds_read_b128 v[178:181], v169
	ds_read_b128 v[182:185], v169 offset:1024
	ds_read_b128 v[186:189], v169 offset:2048
	ds_read_b128 v[190:193], v169 offset:3072
	ds_read_b128 v[194:197], v169 offset:4096
	ds_read_b128 v[198:201], v169 offset:5120
	ds_read_b128 v[202:205], v169 offset:6144
	ds_read_b128 v[206:209], v169 offset:7168
	global_load_lds_dwordx4 v[210:211], off
	v_lshl_add_u64 v[210:211], s[24:25], 0, v[156:157]
	s_add_i32 m0, s41, 0xe000
	s_nop 0
	global_load_lds_dwordx4 v[210:211], off
	s_waitcnt vmcnt(8)
	s_waitcnt lgkmcnt(0)
	s_setprio 1
	s_barrier
	s_waitcnt lgkmcnt(0)
	v_mfma_f32_16x16x32_bf16 v[124:127], v[128:131], v[178:181], v[124:127]
	v_mfma_f32_16x16x32_bf16 v[120:123], v[136:139], v[178:181], v[120:123]
	v_mfma_f32_16x16x32_bf16 v[108:111], v[128:131], v[186:189], v[108:111]
	v_mfma_f32_16x16x32_bf16 v[104:107], v[136:139], v[186:189], v[104:107]
	v_mfma_f32_16x16x32_bf16 v[92:95], v[128:131], v[194:197], v[92:95]
	v_mfma_f32_16x16x32_bf16 v[88:91], v[136:139], v[194:197], v[88:91]
	v_mfma_f32_16x16x32_bf16 v[76:79], v[128:131], v[202:205], v[76:79]
	v_mfma_f32_16x16x32_bf16 v[72:75], v[136:139], v[202:205], v[72:75]
	v_mfma_f32_16x16x32_bf16 v[124:127], v[132:135], v[182:185], v[124:127]
	v_mfma_f32_16x16x32_bf16 v[120:123], v[140:143], v[182:185], v[120:123]
	v_mfma_f32_16x16x32_bf16 v[108:111], v[132:135], v[190:193], v[108:111]
	v_mfma_f32_16x16x32_bf16 v[104:107], v[140:143], v[190:193], v[104:107]
	v_mfma_f32_16x16x32_bf16 v[92:95], v[132:135], v[198:201], v[92:95]
	v_mfma_f32_16x16x32_bf16 v[88:91], v[140:143], v[198:201], v[88:91]
	v_mfma_f32_16x16x32_bf16 v[76:79], v[132:135], v[206:209], v[76:79]
	v_mfma_f32_16x16x32_bf16 v[72:75], v[140:143], v[206:209], v[72:75]
	v_mfma_f32_16x16x32_bf16 v[116:119], v[158:161], v[178:181], v[116:119]
	v_mfma_f32_16x16x32_bf16 v[112:115], v[170:173], v[178:181], v[112:115]
	v_mfma_f32_16x16x32_bf16 v[100:103], v[158:161], v[186:189], v[100:103]
	v_mfma_f32_16x16x32_bf16 v[96:99], v[170:173], v[186:189], v[96:99]
	v_mfma_f32_16x16x32_bf16 v[84:87], v[158:161], v[194:197], v[84:87]
	v_mfma_f32_16x16x32_bf16 v[80:83], v[170:173], v[194:197], v[80:83]
	v_mfma_f32_16x16x32_bf16 v[68:71], v[158:161], v[202:205], v[68:71]
	v_mfma_f32_16x16x32_bf16 v[64:67], v[170:173], v[202:205], v[64:67]
	v_mfma_f32_16x16x32_bf16 v[116:119], v[162:165], v[182:185], v[116:119]
	v_mfma_f32_16x16x32_bf16 v[112:115], v[174:177], v[182:185], v[112:115]
	v_mfma_f32_16x16x32_bf16 v[100:103], v[162:165], v[190:193], v[100:103]
	v_mfma_f32_16x16x32_bf16 v[96:99], v[174:177], v[190:193], v[96:99]
	v_mfma_f32_16x16x32_bf16 v[84:87], v[162:165], v[198:201], v[84:87]
	v_mfma_f32_16x16x32_bf16 v[80:83], v[174:177], v[198:201], v[80:83]
	v_mfma_f32_16x16x32_bf16 v[68:71], v[162:165], v[206:209], v[68:71]
	v_mfma_f32_16x16x32_bf16 v[64:67], v[174:177], v[206:209], v[64:67]
	s_setprio 0
	s_barrier
	s_add_i32 s0, s2, s40
	v_lshl_add_u64 v[210:211], s[26:27], 0, v[144:145]
	s_mov_b32 m0, s0
	ds_read_b128 v[178:181], v169 offset:16384
	ds_read_b128 v[182:185], v169 offset:17408
	ds_read_b128 v[186:189], v169 offset:18432
	ds_read_b128 v[190:193], v169 offset:19456
	ds_read_b128 v[194:197], v169 offset:20480
	ds_read_b128 v[198:201], v169 offset:21504
	ds_read_b128 v[202:205], v169 offset:22528
	ds_read_b128 v[206:209], v169 offset:23552
	global_load_lds_dwordx4 v[210:211], off
	s_add_i32 m0, s0, 0x2000
	s_add_u32 s0, s26, 0x40000
	v_lshl_add_u64 v[212:213], s[26:27], 0, v[152:153]
	s_addc_u32 s1, s27, 0
	s_add_i32 s2, s3, s40
	global_load_lds_dwordx4 v[212:213], off
	v_lshl_add_u64 v[214:215], s[0:1], 0, v[144:145]
	s_mov_b32 m0, s2
	v_lshl_add_u64 v[216:217], s[28:29], 0, v[150:151]
	global_load_lds_dwordx4 v[214:215], off
	v_lshl_add_u64 v[214:215], s[0:1], 0, v[152:153]
	s_add_i32 m0, s2, 0x2000
	s_nop 0
	global_load_lds_dwordx4 v[214:215], off
	v_lshl_add_u64 v[214:215], s[28:29], 0, v[148:149]
	s_mov_b32 m0, s41
	s_nop 0
	global_load_lds_dwordx4 v[214:215], off
	s_mov_b32 m0, s42
	s_nop 0
	global_load_lds_dwordx4 v[216:217], off
	s_waitcnt vmcnt(8)
	s_waitcnt lgkmcnt(0)
	s_setprio 1
	s_barrier
; #define PG8_STAGE(bufoff, gbase, voff) do { _Pragma("unroll") for (int _i = 0; _i < 2; ++_i) \
;         __builtin_amdgcn_global_load_lds((const unsigned*)((const char*)(gbase) + (voff)[_i]), (PG8_LAS unsigned*)(lds + (bufoff) + ldsw + _i * 8192), 16, 0, 0); } while (0)
; #define PG8_LDA(dst, b, h) do { _Pragma("unroll") for (int m = 0; m < 4; ++m) _Pragma("unroll") for (int k = 0; k < 2; ++k) dst[m][k] = *(const PG8_LAS bf16x8*)(lds + PG8_SA(b, h) + aoff + m * 2048 + k * 1024); } while (0)
; #define PG8_LDB(dst, b, h) do { _Pragma("unroll") for (int n = 0; n < 2; ++n) _Pragma("unroll") for (int k = 0; k < 2; ++k) dst[n][k] = *(const PG8_LAS bf16x8*)(lds + PG8_SB(b, h) + boff + n * 2048 + k * 1024); } while (0)
; #define PG8_MMA(ai, bj, At, Bt) do { __builtin_amdgcn_s_setprio(1); _Pragma("unroll") for (int m = 0; m < 4; ++m) _Pragma("unroll") for (int n = 0; n < 2; ++n) _Pragma("unroll") for (int k = 0; k < 2; ++k) \
;         acc[ai][bj][m][n] = __builtin_amdgcn_mfma_f32_16x16x32_bf16(Bt[n][k], At[m][k], acc[ai][bj][m][n], 0, 0, 0); __builtin_amdgcn_s_setprio(0); } while (0)
; #define PG8_WAIT_V(n) asm volatile("s_waitcnt vmcnt(" #n ")" ::: "memory")
; #define PG8_WAIT_L(n) asm volatile("s_waitcnt lgkmcnt(" #n ")" ::: "memory")
; #define PG8_BAR __builtin_amdgcn_s_barrier()
; #define PG8_SCHED __builtin_amdgcn_sched_barrier(0)
; template <class Epi, class Sched, bool ALIGN_EPI = false, bool SP2 = false>
; __device__ __forceinline__ void gemm_phase(PG8_LAS unsigned char* lds, const Gemm g, const Sched& S, const Epi& E, int tid_in) {
;     ...
;             PG8_LDA(At, 0, 1); PG8_STAGE(PG8_SB(0, 0), b2, voffB); PG8_STAGE(PG8_SB(0, 1), b2 + hstep, voffB); PG8_STAGE(PG8_SA(0, 0), a2, voffA);
;             PG8_WAIT_V(8); PG8_WAIT_L(0); PG8_BAR; PG8_MMA(1, 0, At, B0); PG8_MMA(1, 1, At, B1); PG8_BAR; PG8_SCHED;
;             PG8_LDB(B0, 1, 0); PG8_LDB(B1, 1, 1); PG8_SCHED; PG8_LDA(At, 1, 0); PG8_STAGE(PG8_SA(0, 1), a2 + hstep, voffA);
;             PG8_WAIT_V(8); PG8_WAIT_L(0); PG8_BAR; PG8_MMA(0, 0, At, B0); PG8_MMA(0, 1, At, B1); PG8_BAR; PG8_SCHED;
	s_waitcnt lgkmcnt(0)
	v_mfma_f32_16x16x32_bf16 v[60:63], v[128:131], v[178:181], v[60:63]
	v_mfma_f32_16x16x32_bf16 v[56:59], v[136:139], v[178:181], v[56:59]
	v_mfma_f32_16x16x32_bf16 v[44:47], v[128:131], v[186:189], v[44:47]
	v_mfma_f32_16x16x32_bf16 v[40:43], v[136:139], v[186:189], v[40:43]
	v_mfma_f32_16x16x32_bf16 v[28:31], v[128:131], v[194:197], v[28:31]
	v_mfma_f32_16x16x32_bf16 v[24:27], v[136:139], v[194:197], v[24:27]
	v_mfma_f32_16x16x32_bf16 v[12:15], v[128:131], v[202:205], v[12:15]
	v_mfma_f32_16x16x32_bf16 v[8:11], v[136:139], v[202:205], v[8:11]
	v_mfma_f32_16x16x32_bf16 v[60:63], v[132:135], v[182:185], v[60:63]
	v_mfma_f32_16x16x32_bf16 v[56:59], v[140:143], v[182:185], v[56:59]
	v_mfma_f32_16x16x32_bf16 v[44:47], v[132:135], v[190:193], v[44:47]
	v_mfma_f32_16x16x32_bf16 v[40:43], v[140:143], v[190:193], v[40:43]
	v_mfma_f32_16x16x32_bf16 v[28:31], v[132:135], v[198:201], v[28:31]
	v_mfma_f32_16x16x32_bf16 v[24:27], v[140:143], v[198:201], v[24:27]
	v_mfma_f32_16x16x32_bf16 v[12:15], v[132:135], v[206:209], v[12:15]
	v_mfma_f32_16x16x32_bf16 v[8:11], v[140:143], v[206:209], v[8:11]
	v_mfma_f32_16x16x32_bf16 v[52:55], v[158:161], v[178:181], v[52:55]
	v_mfma_f32_16x16x32_bf16 v[48:51], v[170:173], v[178:181], v[48:51]
	v_mfma_f32_16x16x32_bf16 v[36:39], v[158:161], v[186:189], v[36:39]
	v_mfma_f32_16x16x32_bf16 v[32:35], v[170:173], v[186:189], v[32:35]
	v_mfma_f32_16x16x32_bf16 v[20:23], v[158:161], v[194:197], v[20:23]
	v_mfma_f32_16x16x32_bf16 v[16:19], v[170:173], v[194:197], v[16:19]
	v_mfma_f32_16x16x32_bf16 v[4:7], v[158:161], v[202:205], v[4:7]
	v_mfma_f32_16x16x32_bf16 v[0:3], v[170:173], v[202:205], v[0:3]
	v_mfma_f32_16x16x32_bf16 v[52:55], v[162:165], v[182:185], v[52:55]
	v_mfma_f32_16x16x32_bf16 v[48:51], v[174:177], v[182:185], v[48:51]
	v_mfma_f32_16x16x32_bf16 v[36:39], v[162:165], v[190:193], v[36:39]
	v_mfma_f32_16x16x32_bf16 v[32:35], v[174:177], v[190:193], v[32:35]
	v_mfma_f32_16x16x32_bf16 v[20:23], v[162:165], v[198:201], v[20:23]
	v_mfma_f32_16x16x32_bf16 v[16:19], v[174:177], v[198:201], v[16:19]
	v_mfma_f32_16x16x32_bf16 v[4:7], v[162:165], v[206:209], v[4:7]
	v_mfma_f32_16x16x32_bf16 v[0:3], v[174:177], v[206:209], v[0:3]
	s_setprio 0
	s_barrier
	s_add_i32 s2, 0, 0x18000
	s_add_i32 s3, 0, 0x1c000
	v_add_u32_e32 v140, s2, v168
	v_add_u32_e32 v174, s3, v168
	ds_read_b128 v[128:131], v140
	ds_read_b128 v[132:135], v140 offset:1024
	ds_read_b128 v[136:139], v140 offset:2048
	ds_read_b128 v[140:143], v140 offset:3072
	ds_read_b128 v[158:161], v174
	ds_read_b128 v[162:165], v174 offset:1024
	ds_read_b128 v[170:173], v174 offset:2048
	ds_read_b128 v[174:177], v174 offset:3072
	s_add_u32 s0, s28, 0x40000
	s_addc_u32 s1, s29, 0
	s_mov_b32 m0, s43
	v_lshl_add_u64 v[218:219], s[0:1], 0, v[148:149]
	ds_read_b128 v[178:181], v169 offset:32768
	ds_read_b128 v[182:185], v169 offset:33792
	ds_read_b128 v[186:189], v169 offset:34816
	ds_read_b128 v[190:193], v169 offset:35840
	ds_read_b128 v[194:197], v169 offset:36864
	ds_read_b128 v[198:201], v169 offset:37888
	ds_read_b128 v[202:205], v169 offset:38912
	ds_read_b128 v[206:209], v169 offset:39936
	global_load_lds_dwordx4 v[218:219], off
	v_lshl_add_u64 v[218:219], s[0:1], 0, v[150:151]
	s_mov_b32 m0, s44
	s_nop 0
	global_load_lds_dwordx4 v[218:219], off
	s_waitcnt vmcnt(8)
	s_waitcnt lgkmcnt(0)
	s_setprio 1
	s_barrier
	s_waitcnt lgkmcnt(0)
	v_mfma_f32_16x16x32_bf16 v[124:127], v[128:131], v[178:181], v[124:127]
	v_mfma_f32_16x16x32_bf16 v[120:123], v[136:139], v[178:181], v[120:123]
	v_mfma_f32_16x16x32_bf16 v[108:111], v[128:131], v[186:189], v[108:111]
	v_mfma_f32_16x16x32_bf16 v[104:107], v[136:139], v[186:189], v[104:107]
	v_mfma_f32_16x16x32_bf16 v[92:95], v[128:131], v[194:197], v[92:95]
	v_mfma_f32_16x16x32_bf16 v[88:91], v[136:139], v[194:197], v[88:91]
	v_mfma_f32_16x16x32_bf16 v[76:79], v[128:131], v[202:205], v[76:79]
	v_mfma_f32_16x16x32_bf16 v[72:75], v[136:139], v[202:205], v[72:75]
	v_mfma_f32_16x16x32_bf16 v[124:127], v[132:135], v[182:185], v[124:127]
	v_mfma_f32_16x16x32_bf16 v[120:123], v[140:143], v[182:185], v[120:123]
	v_mfma_f32_16x16x32_bf16 v[108:111], v[132:135], v[190:193], v[108:111]
	v_mfma_f32_16x16x32_bf16 v[104:107], v[140:143], v[190:193], v[104:107]
	v_mfma_f32_16x16x32_bf16 v[92:95], v[132:135], v[198:201], v[92:95]
	v_mfma_f32_16x16x32_bf16 v[88:91], v[140:143], v[198:201], v[88:91]
	v_mfma_f32_16x16x32_bf16 v[76:79], v[132:135], v[206:209], v[76:79]
	v_mfma_f32_16x16x32_bf16 v[72:75], v[140:143], v[206:209], v[72:75]
	v_mfma_f32_16x16x32_bf16 v[116:119], v[158:161], v[178:181], v[116:119]
	v_mfma_f32_16x16x32_bf16 v[112:115], v[170:173], v[178:181], v[112:115]
	v_mfma_f32_16x16x32_bf16 v[100:103], v[158:161], v[186:189], v[100:103]
	v_mfma_f32_16x16x32_bf16 v[96:99], v[170:173], v[186:189], v[96:99]
	v_mfma_f32_16x16x32_bf16 v[84:87], v[158:161], v[194:197], v[84:87]
	v_mfma_f32_16x16x32_bf16 v[80:83], v[170:173], v[194:197], v[80:83]
	v_mfma_f32_16x16x32_bf16 v[68:71], v[158:161], v[202:205], v[68:71]
	v_mfma_f32_16x16x32_bf16 v[64:67], v[170:173], v[202:205], v[64:67]
	v_mfma_f32_16x16x32_bf16 v[116:119], v[162:165], v[182:185], v[116:119]
	v_mfma_f32_16x16x32_bf16 v[112:115], v[174:177], v[182:185], v[112:115]
	v_mfma_f32_16x16x32_bf16 v[100:103], v[162:165], v[190:193], v[100:103]
	v_mfma_f32_16x16x32_bf16 v[96:99], v[174:177], v[190:193], v[96:99]
	v_mfma_f32_16x16x32_bf16 v[84:87], v[162:165], v[198:201], v[84:87]
	v_mfma_f32_16x16x32_bf16 v[80:83], v[174:177], v[198:201], v[80:83]
	v_mfma_f32_16x16x32_bf16 v[68:71], v[162:165], v[206:209], v[68:71]
	v_mfma_f32_16x16x32_bf16 v[64:67], v[174:177], v[206:209], v[64:67]
	s_setprio 0
	s_barrier
; #define PG8_STAGE(bufoff, gbase, voff) do { _Pragma("unroll") for (int _i = 0; _i < 2; ++_i) \
;         __builtin_amdgcn_global_load_lds((const unsigned*)((const char*)(gbase) + (voff)[_i]), (PG8_LAS unsigned*)(lds + (bufoff) + ldsw + _i * 8192), 16, 0, 0); } while (0)
; #define PG8_LDA(dst, b, h) do { _Pragma("unroll") for (int m = 0; m < 4; ++m) _Pragma("unroll") for (int k = 0; k < 2; ++k) dst[m][k] = *(const PG8_LAS bf16x8*)(lds + PG8_SA(b, h) + aoff + m * 2048 + k * 1024); } while (0)
; #define PG8_MMA(ai, bj, At, Bt) do { __builtin_amdgcn_s_setprio(1); _Pragma("unroll") for (int m = 0; m < 4; ++m) _Pragma("unroll") for (int n = 0; n < 2; ++n) _Pragma("unroll") for (int k = 0; k < 2; ++k) \
;         acc[ai][bj][m][n] = __builtin_amdgcn_mfma_f32_16x16x32_bf16(Bt[n][k], At[m][k], acc[ai][bj][m][n], 0, 0, 0); __builtin_amdgcn_s_setprio(0); } while (0)
; #define PG8_WAIT_V(n) asm volatile("s_waitcnt vmcnt(" #n ")" ::: "memory")
; #define PG8_WAIT_L(n) asm volatile("s_waitcnt lgkmcnt(" #n ")" ::: "memory")
; #define PG8_BAR __builtin_amdgcn_s_barrier()
; #define PG8_SCHED __builtin_amdgcn_sched_barrier(0)
; template <class Epi, class Sched, bool ALIGN_EPI = false, bool SP2 = false>
; __device__ __forceinline__ void gemm_phase(PG8_LAS unsigned char* lds, const Gemm g, const Sched& S, const Epi& E, int tid_in) {
;     ...
;             PG8_LDA(At, 1, 1); PG8_STAGE(PG8_SB(1, 0), b3, voffB); PG8_STAGE(PG8_SB(1, 1), b3 + hstep, voffB); PG8_STAGE(PG8_SA(1, 0), a3, voffA);
;             PG8_WAIT_V(8); PG8_WAIT_L(0); PG8_BAR; PG8_MMA(1, 0, At, B0); PG8_MMA(1, 1, At, B1); PG8_BAR; PG8_SCHED;
	s_add_i32 s0, s2, s40
	v_lshl_add_u64 v[210:211], v[210:211], 0, s[68:69]
	s_mov_b32 m0, s0
	ds_read_b128 v[178:181], v169 offset:49152
	ds_read_b128 v[182:185], v169 offset:50176
	ds_read_b128 v[186:189], v169 offset:51200
	ds_read_b128 v[190:193], v169 offset:52224
	ds_read_b128 v[194:197], v169 offset:53248
	ds_read_b128 v[198:201], v169 offset:54272
	ds_read_b128 v[202:205], v169 offset:55296
	ds_read_b128 v[206:209], v169 offset:56320
	global_load_lds_dwordx4 v[210:211], off
	s_add_i32 m0, s0, 0x2000
	s_add_u32 s0, s26, 0x40080
	v_lshl_add_u64 v[210:211], v[212:213], 0, s[68:69]
	s_addc_u32 s1, s27, 0
	s_add_i32 s2, s3, s40
	global_load_lds_dwordx4 v[210:211], off
	v_lshl_add_u64 v[210:211], s[0:1], 0, v[144:145]
	s_mov_b32 m0, s2
	s_nop 0
	global_load_lds_dwordx4 v[210:211], off
	v_lshl_add_u64 v[210:211], s[0:1], 0, v[152:153]
	s_add_i32 m0, s2, 0x2000
	s_nop 0
	global_load_lds_dwordx4 v[210:211], off
	v_lshl_add_u64 v[210:211], v[214:215], 0, s[68:69]
	s_mov_b32 m0, s50
	s_nop 0
	global_load_lds_dwordx4 v[210:211], off
	v_lshl_add_u64 v[210:211], v[216:217], 0, s[68:69]
	s_mov_b32 m0, s51
	s_nop 0
	global_load_lds_dwordx4 v[210:211], off
	s_waitcnt vmcnt(8)
	s_waitcnt lgkmcnt(0)
	s_setprio 1
	s_barrier
	s_waitcnt lgkmcnt(0)
	v_mfma_f32_16x16x32_bf16 v[60:63], v[128:131], v[178:181], v[60:63]
	v_mfma_f32_16x16x32_bf16 v[56:59], v[136:139], v[178:181], v[56:59]
	v_mfma_f32_16x16x32_bf16 v[44:47], v[128:131], v[186:189], v[44:47]
	v_mfma_f32_16x16x32_bf16 v[40:43], v[136:139], v[186:189], v[40:43]
	v_mfma_f32_16x16x32_bf16 v[28:31], v[128:131], v[194:197], v[28:31]
	v_mfma_f32_16x16x32_bf16 v[24:27], v[136:139], v[194:197], v[24:27]
	v_mfma_f32_16x16x32_bf16 v[12:15], v[128:131], v[202:205], v[12:15]
	v_mfma_f32_16x16x32_bf16 v[8:11], v[136:139], v[202:205], v[8:11]
	v_mfma_f32_16x16x32_bf16 v[60:63], v[132:135], v[182:185], v[60:63]
	v_mfma_f32_16x16x32_bf16 v[56:59], v[140:143], v[182:185], v[56:59]
	v_mfma_f32_16x16x32_bf16 v[44:47], v[132:135], v[190:193], v[44:47]
	v_mfma_f32_16x16x32_bf16 v[40:43], v[140:143], v[190:193], v[40:43]
	v_mfma_f32_16x16x32_bf16 v[28:31], v[132:135], v[198:201], v[28:31]
	v_mfma_f32_16x16x32_bf16 v[24:27], v[140:143], v[198:201], v[24:27]
	v_mfma_f32_16x16x32_bf16 v[12:15], v[132:135], v[206:209], v[12:15]
	v_mfma_f32_16x16x32_bf16 v[8:11], v[140:143], v[206:209], v[8:11]
	v_mfma_f32_16x16x32_bf16 v[52:55], v[158:161], v[178:181], v[52:55]
	v_mfma_f32_16x16x32_bf16 v[48:51], v[170:173], v[178:181], v[48:51]
	v_mfma_f32_16x16x32_bf16 v[36:39], v[158:161], v[186:189], v[36:39]
	v_mfma_f32_16x16x32_bf16 v[32:35], v[170:173], v[186:189], v[32:35]
	v_mfma_f32_16x16x32_bf16 v[20:23], v[158:161], v[194:197], v[20:23]
	v_mfma_f32_16x16x32_bf16 v[16:19], v[170:173], v[194:197], v[16:19]
	v_mfma_f32_16x16x32_bf16 v[4:7], v[158:161], v[202:205], v[4:7]
	v_mfma_f32_16x16x32_bf16 v[0:3], v[170:173], v[202:205], v[0:3]
	v_mfma_f32_16x16x32_bf16 v[52:55], v[162:165], v[182:185], v[52:55]
	v_mfma_f32_16x16x32_bf16 v[48:51], v[174:177], v[182:185], v[48:51]
	v_mfma_f32_16x16x32_bf16 v[36:39], v[162:165], v[190:193], v[36:39]
	v_mfma_f32_16x16x32_bf16 v[32:35], v[174:177], v[190:193], v[32:35]
	v_mfma_f32_16x16x32_bf16 v[20:23], v[162:165], v[198:201], v[20:23]
	v_mfma_f32_16x16x32_bf16 v[16:19], v[174:177], v[198:201], v[16:19]
	v_mfma_f32_16x16x32_bf16 v[4:7], v[162:165], v[206:209], v[4:7]
	v_mfma_f32_16x16x32_bf16 v[0:3], v[174:177], v[206:209], v[0:3]
	s_setprio 0
	s_barrier
	s_add_i32 s55, s55, 2
	s_add_u32 s24, s24, 0x100
	s_addc_u32 s25, s25, 0
	s_add_u32 s53, s53, 0x100
	s_addc_u32 s54, s54, 0
	s_cmp_gt_u32 s55, 13
	s_cbranch_scc0 .LBB0_219
	s_and_b64 vcc, exec, s[14:15]
	s_cbranch_vccz .LBB0_222
	s_barrier

; #define PG8_STAGE(bufoff, gbase, voff) do { _Pragma("unroll") for (int _i = 0; _i < 2; ++_i) \
;         __builtin_amdgcn_global_load_lds((const unsigned*)((const char*)(gbase) + (voff)[_i]), (PG8_LAS unsigned*)(lds + (bufoff) + ldsw + _i * 8192), 16, 0, 0); } while (0)
; #define PG8_LDA(dst, b, h) do { _Pragma("unroll") for (int m = 0; m < 4; ++m) _Pragma("unroll") for (int k = 0; k < 2; ++k) dst[m][k] = *(const PG8_LAS bf16x8*)(lds + PG8_SA(b, h) + aoff + m * 2048 + k * 1024); } while (0)
; #define PG8_LDB(dst, b, h) do { _Pragma("unroll") for (int n = 0; n < 2; ++n) _Pragma("unroll") for (int k = 0; k < 2; ++k) dst[n][k] = *(const PG8_LAS bf16x8*)(lds + PG8_SB(b, h) + boff + n * 2048 + k * 1024); } while (0)
; #define PG8_MMA(ai, bj, At, Bt) do { __builtin_amdgcn_s_setprio(1); _Pragma("unroll") for (int m = 0; m < 4; ++m) _Pragma("unroll") for (int n = 0; n < 2; ++n) _Pragma("unroll") for (int k = 0; k < 2; ++k) \
;         acc[ai][bj][m][n] = __builtin_amdgcn_mfma_f32_16x16x32_bf16(Bt[n][k], At[m][k], acc[ai][bj][m][n], 0, 0, 0); __builtin_amdgcn_s_setprio(0); } while (0)
; #define PG8_WAIT_V(n) asm volatile("s_waitcnt vmcnt(" #n ")" ::: "memory")
; #define PG8_WAIT_L(n) asm volatile("s_waitcnt lgkmcnt(" #n ")" ::: "memory")
; #define PG8_BAR __builtin_amdgcn_s_barrier()
; template <class Epi, class Sched, bool ALIGN_EPI = false, bool SP2 = false>
; __device__ __forceinline__ void gemm_phase(PG8_LAS unsigned char* lds, const Gemm g, const Sched& S, const Epi& E, int tid_in) {
;     ...
;         const int nt = cur.nk ? cur.nk : nt_all;
;         for (int t = 0; t < nt; t += 2) {
;             const bool last = (t == nt - 2);
;             const char* a1 = cA + (size_t)(t + 1) * kstep;
;             const char* a2 = last ? nA : cA + (size_t)(t + 2) * kstep; const char* b2 = last ? nB : cB + (size_t)(t + 2) * kstep;
;             const char* a3 = a2 + kstep; const char* b3 = b2 + kstep;
;             if (last && has_next) S.a_ready(nxt);
;             if constexpr (SP2) {
;             PG8_LDB(B0, 0, 0); PG8_LDB(B1, 0, 1); PG8_SCHED; PG8_LDA(At, 0, 0); PG8_STAGE(PG8_SA(1, 1), a1 + hstep, voffA);
;             PG8_WAIT_V(8); PG8_WAIT_L(0); PG8_BAR; PG8_MMA(0, 0, At, B0); PG8_MMA(0, 1, At, B1); PG8_BAR; PG8_SCHED;
;             PG8_LDA(At, 0, 1); PG8_STAGE(PG8_SB(0, 0), b2, voffB); PG8_STAGE(PG8_SB(0, 1), b2 + hstep, voffB); PG8_STAGE(PG8_SA(0, 0), a2, voffA);
.LBB0_307:
	s_add_i32 s1, s0, 2
	s_add_u32 s26, s24, 0x80
	s_addc_u32 s27, s25, 0
	s_add_i32 s33, 0, 0x10000
	s_cmp_eq_u32 s67, s0
	s_cselect_b32 s27, s19, s27
	s_cselect_b32 s26, s18, s26
	v_add_u32_e32 v143, s33, v232
	s_cselect_b32 s71, s21, s69
	s_cselect_b32 s70, s20, s68
	s_add_i32 s0, 0, 0x14000
	s_waitcnt lgkmcnt(0)
	ds_read_b128 v[128:131], v143
	ds_read_b128 v[132:135], v143 offset:1024
	ds_read_b128 v[154:157], v143 offset:2048
	ds_read_b128 v[158:161], v143 offset:3072
	v_add_u32_e32 v143, s0, v232
	ds_read_b128 v[162:165], v143
	ds_read_b128 v[166:169], v143 offset:1024
	ds_read_b128 v[170:173], v143 offset:2048
	ds_read_b128 v[174:177], v143 offset:3072
	v_lshl_add_u64 v[210:211], s[24:25], 0, v[150:151]
	s_add_i32 m0, s23, 0xc000
	ds_read_b128 v[178:181], v233
	ds_read_b128 v[182:185], v233 offset:1024
	ds_read_b128 v[186:189], v233 offset:2048
	ds_read_b128 v[190:193], v233 offset:3072
	ds_read_b128 v[194:197], v233 offset:4096
	ds_read_b128 v[198:201], v233 offset:5120
	ds_read_b128 v[202:205], v233 offset:6144
	ds_read_b128 v[206:209], v233 offset:7168
	global_load_lds_dwordx4 v[210:211], off
	v_lshl_add_u64 v[210:211], s[24:25], 0, v[152:153]
	s_add_i32 m0, s23, 0xe000
	s_nop 0
	global_load_lds_dwordx4 v[210:211], off
	s_waitcnt vmcnt(8)
	s_waitcnt lgkmcnt(0)
	s_setprio 1
	s_barrier
	s_waitcnt lgkmcnt(0)
	v_mfma_f32_16x16x32_bf16 v[124:127], v[128:131], v[178:181], v[124:127]
	v_mfma_f32_16x16x32_bf16 v[120:123], v[154:157], v[178:181], v[120:123]
	v_mfma_f32_16x16x32_bf16 v[116:119], v[128:131], v[186:189], v[116:119]
	v_mfma_f32_16x16x32_bf16 v[112:115], v[154:157], v[186:189], v[112:115]
	v_mfma_f32_16x16x32_bf16 v[108:111], v[128:131], v[194:197], v[108:111]
	v_mfma_f32_16x16x32_bf16 v[104:107], v[154:157], v[194:197], v[104:107]
	v_mfma_f32_16x16x32_bf16 v[100:103], v[128:131], v[202:205], v[100:103]
	v_mfma_f32_16x16x32_bf16 v[96:99], v[154:157], v[202:205], v[96:99]
	v_mfma_f32_16x16x32_bf16 v[124:127], v[132:135], v[182:185], v[124:127]
	v_mfma_f32_16x16x32_bf16 v[120:123], v[158:161], v[182:185], v[120:123]
	v_mfma_f32_16x16x32_bf16 v[116:119], v[132:135], v[190:193], v[116:119]
	v_mfma_f32_16x16x32_bf16 v[112:115], v[158:161], v[190:193], v[112:115]
	v_mfma_f32_16x16x32_bf16 v[108:111], v[132:135], v[198:201], v[108:111]
	v_mfma_f32_16x16x32_bf16 v[104:107], v[158:161], v[198:201], v[104:107]
	v_mfma_f32_16x16x32_bf16 v[100:103], v[132:135], v[206:209], v[100:103]
	v_mfma_f32_16x16x32_bf16 v[96:99], v[158:161], v[206:209], v[96:99]
	v_mfma_f32_16x16x32_bf16 v[60:63], v[162:165], v[178:181], v[60:63]
	v_mfma_f32_16x16x32_bf16 v[56:59], v[170:173], v[178:181], v[56:59]
	v_mfma_f32_16x16x32_bf16 v[52:55], v[162:165], v[186:189], v[52:55]
	v_mfma_f32_16x16x32_bf16 v[48:51], v[170:173], v[186:189], v[48:51]
	v_mfma_f32_16x16x32_bf16 v[44:47], v[162:165], v[194:197], v[44:47]
	v_mfma_f32_16x16x32_bf16 v[40:43], v[170:173], v[194:197], v[40:43]
	v_mfma_f32_16x16x32_bf16 v[36:39], v[162:165], v[202:205], v[36:39]
	v_mfma_f32_16x16x32_bf16 v[32:35], v[170:173], v[202:205], v[32:35]
	v_mfma_f32_16x16x32_bf16 v[60:63], v[166:169], v[182:185], v[60:63]
	v_mfma_f32_16x16x32_bf16 v[56:59], v[174:177], v[182:185], v[56:59]
	v_mfma_f32_16x16x32_bf16 v[52:55], v[166:169], v[190:193], v[52:55]
	v_mfma_f32_16x16x32_bf16 v[48:51], v[174:177], v[190:193], v[48:51]
	v_mfma_f32_16x16x32_bf16 v[44:47], v[166:169], v[198:201], v[44:47]
	v_mfma_f32_16x16x32_bf16 v[40:43], v[174:177], v[198:201], v[40:43]
	v_mfma_f32_16x16x32_bf16 v[36:39], v[166:169], v[206:209], v[36:39]
	v_mfma_f32_16x16x32_bf16 v[32:35], v[174:177], v[206:209], v[32:35]
	s_setprio 0
	s_barrier
	s_add_i32 s33, s33, s31
	v_lshl_add_u64 v[210:211], s[70:71], 0, v[144:145]
	s_mov_b32 m0, s33
	ds_read_b128 v[178:181], v233 offset:16384
	ds_read_b128 v[182:185], v233 offset:17408
	ds_read_b128 v[186:189], v233 offset:18432
	ds_read_b128 v[190:193], v233 offset:19456
	ds_read_b128 v[194:197], v233 offset:20480
	ds_read_b128 v[198:201], v233 offset:21504
	ds_read_b128 v[202:205], v233 offset:22528
	ds_read_b128 v[206:209], v233 offset:23552
	global_load_lds_dwordx4 v[210:211], off
	s_add_i32 m0, s33, 0x2000
	v_lshl_add_u64 v[212:213], s[70:71], 0, v[140:141]
	s_add_u32 s70, s70, s90
	s_addc_u32 s71, s71, 0
	s_add_i32 s0, s0, s31
	global_load_lds_dwordx4 v[212:213], off
	v_lshl_add_u64 v[214:215], s[70:71], 0, v[144:145]
	s_mov_b32 m0, s0
	v_lshl_add_u64 v[216:217], s[70:71], 0, v[140:141]
	global_load_lds_dwordx4 v[214:215], off
	s_add_i32 m0, s0, 0x2000
	v_lshl_add_u64 v[218:219], s[26:27], 0, v[136:137]
	global_load_lds_dwordx4 v[216:217], off
	s_mov_b32 m0, s23
	v_lshl_add_u64 v[234:235], s[26:27], 0, v[138:139]
	global_load_lds_dwordx4 v[218:219], off
	s_mov_b32 m0, s41
	s_nop 0
	global_load_lds_dwordx4 v[234:235], off
	s_waitcnt vmcnt(8)
	s_waitcnt lgkmcnt(0)
	s_setprio 1
	s_barrier
; #define PG8_STAGE(bufoff, gbase, voff) do { _Pragma("unroll") for (int _i = 0; _i < 2; ++_i) \
;         __builtin_amdgcn_global_load_lds((const unsigned*)((const char*)(gbase) + (voff)[_i]), (PG8_LAS unsigned*)(lds + (bufoff) + ldsw + _i * 8192), 16, 0, 0); } while (0)
; #define PG8_LDA(dst, b, h) do { _Pragma("unroll") for (int m = 0; m < 4; ++m) _Pragma("unroll") for (int k = 0; k < 2; ++k) dst[m][k] = *(const PG8_LAS bf16x8*)(lds + PG8_SA(b, h) + aoff + m * 2048 + k * 1024); } while (0)
; #define PG8_LDB(dst, b, h) do { _Pragma("unroll") for (int n = 0; n < 2; ++n) _Pragma("unroll") for (int k = 0; k < 2; ++k) dst[n][k] = *(const PG8_LAS bf16x8*)(lds + PG8_SB(b, h) + boff + n * 2048 + k * 1024); } while (0)
; #define PG8_MMA(ai, bj, At, Bt) do { __builtin_amdgcn_s_setprio(1); _Pragma("unroll") for (int m = 0; m < 4; ++m) _Pragma("unroll") for (int n = 0; n < 2; ++n) _Pragma("unroll") for (int k = 0; k < 2; ++k) \
;         acc[ai][bj][m][n] = __builtin_amdgcn_mfma_f32_16x16x32_bf16(Bt[n][k], At[m][k], acc[ai][bj][m][n], 0, 0, 0); __builtin_amdgcn_s_setprio(0); } while (0)
; #define PG8_WAIT_V(n) asm volatile("s_waitcnt vmcnt(" #n ")" ::: "memory")
; #define PG8_WAIT_L(n) asm volatile("s_waitcnt lgkmcnt(" #n ")" ::: "memory")
; #define PG8_BAR __builtin_amdgcn_s_barrier()
; #define PG8_SCHED __builtin_amdgcn_sched_barrier(0)
; template <class Epi, class Sched, bool ALIGN_EPI = false, bool SP2 = false>
; __device__ __forceinline__ void gemm_phase(PG8_LAS unsigned char* lds, const Gemm g, const Sched& S, const Epi& E, int tid_in) {
;     ...
;             PG8_LDA(At, 0, 1); PG8_STAGE(PG8_SB(0, 0), b2, voffB); PG8_STAGE(PG8_SB(0, 1), b2 + hstep, voffB); PG8_STAGE(PG8_SA(0, 0), a2, voffA);
;             PG8_WAIT_V(8); PG8_WAIT_L(0); PG8_BAR; PG8_MMA(1, 0, At, B0); PG8_MMA(1, 1, At, B1); PG8_BAR; PG8_SCHED;
;             PG8_LDB(B0, 1, 0); PG8_LDB(B1, 1, 1); PG8_SCHED; PG8_LDA(At, 1, 0); PG8_STAGE(PG8_SA(0, 1), a2 + hstep, voffA);
;             PG8_WAIT_V(8); PG8_WAIT_L(0); PG8_BAR; PG8_MMA(0, 0, At, B0); PG8_MMA(0, 1, At, B1); PG8_BAR; PG8_SCHED;
	s_waitcnt lgkmcnt(0)
	v_mfma_f32_16x16x32_bf16 v[92:95], v[128:131], v[178:181], v[92:95]
	v_mfma_f32_16x16x32_bf16 v[88:91], v[154:157], v[178:181], v[88:91]
	v_mfma_f32_16x16x32_bf16 v[84:87], v[128:131], v[186:189], v[84:87]
	v_mfma_f32_16x16x32_bf16 v[80:83], v[154:157], v[186:189], v[80:83]
	v_mfma_f32_16x16x32_bf16 v[76:79], v[128:131], v[194:197], v[76:79]
	v_mfma_f32_16x16x32_bf16 v[72:75], v[154:157], v[194:197], v[72:75]
	v_mfma_f32_16x16x32_bf16 v[68:71], v[128:131], v[202:205], v[68:71]
	v_mfma_f32_16x16x32_bf16 v[64:67], v[154:157], v[202:205], v[64:67]
	v_mfma_f32_16x16x32_bf16 v[92:95], v[132:135], v[182:185], v[92:95]
	v_mfma_f32_16x16x32_bf16 v[88:91], v[158:161], v[182:185], v[88:91]
	v_mfma_f32_16x16x32_bf16 v[84:87], v[132:135], v[190:193], v[84:87]
	v_mfma_f32_16x16x32_bf16 v[80:83], v[158:161], v[190:193], v[80:83]
	v_mfma_f32_16x16x32_bf16 v[76:79], v[132:135], v[198:201], v[76:79]
	v_mfma_f32_16x16x32_bf16 v[72:75], v[158:161], v[198:201], v[72:75]
	v_mfma_f32_16x16x32_bf16 v[68:71], v[132:135], v[206:209], v[68:71]
	v_mfma_f32_16x16x32_bf16 v[64:67], v[158:161], v[206:209], v[64:67]
	v_mfma_f32_16x16x32_bf16 v[28:31], v[162:165], v[178:181], v[28:31]
	v_mfma_f32_16x16x32_bf16 v[24:27], v[170:173], v[178:181], v[24:27]
	v_mfma_f32_16x16x32_bf16 v[20:23], v[162:165], v[186:189], v[20:23]
	v_mfma_f32_16x16x32_bf16 v[16:19], v[170:173], v[186:189], v[16:19]
	v_mfma_f32_16x16x32_bf16 v[12:15], v[162:165], v[194:197], v[12:15]
	v_mfma_f32_16x16x32_bf16 v[8:11], v[170:173], v[194:197], v[8:11]
	v_mfma_f32_16x16x32_bf16 v[4:7], v[162:165], v[202:205], v[4:7]
	v_mfma_f32_16x16x32_bf16 v[0:3], v[170:173], v[202:205], v[0:3]
	v_mfma_f32_16x16x32_bf16 v[28:31], v[166:169], v[182:185], v[28:31]
	v_mfma_f32_16x16x32_bf16 v[24:27], v[174:177], v[182:185], v[24:27]
	v_mfma_f32_16x16x32_bf16 v[20:23], v[166:169], v[190:193], v[20:23]
	v_mfma_f32_16x16x32_bf16 v[16:19], v[174:177], v[190:193], v[16:19]
	v_mfma_f32_16x16x32_bf16 v[12:15], v[166:169], v[198:201], v[12:15]
	v_mfma_f32_16x16x32_bf16 v[8:11], v[174:177], v[198:201], v[8:11]
	v_mfma_f32_16x16x32_bf16 v[4:7], v[166:169], v[206:209], v[4:7]
	v_mfma_f32_16x16x32_bf16 v[0:3], v[174:177], v[206:209], v[0:3]
	s_setprio 0
	s_barrier
	s_add_i32 s0, 0, 0x18000
	v_add_u32_e32 v143, s0, v232
	s_add_i32 s33, 0, 0x1c000
	ds_read_b128 v[128:131], v143
	ds_read_b128 v[132:135], v143 offset:1024
	ds_read_b128 v[154:157], v143 offset:2048
	ds_read_b128 v[158:161], v143 offset:3072
	v_add_u32_e32 v143, s33, v232
	ds_read_b128 v[162:165], v143
	ds_read_b128 v[166:169], v143 offset:1024
	ds_read_b128 v[170:173], v143 offset:2048
	ds_read_b128 v[174:177], v143 offset:3072
	s_add_u32 s26, s26, s90
	s_addc_u32 s27, s27, 0
	s_mov_b32 m0, s42
	v_lshl_add_u64 v[236:237], s[26:27], 0, v[136:137]
	ds_read_b128 v[178:181], v233 offset:32768
	ds_read_b128 v[182:185], v233 offset:33792
	ds_read_b128 v[186:189], v233 offset:34816
	ds_read_b128 v[190:193], v233 offset:35840
	ds_read_b128 v[194:197], v233 offset:36864
	ds_read_b128 v[198:201], v233 offset:37888
	ds_read_b128 v[202:205], v233 offset:38912
	ds_read_b128 v[206:209], v233 offset:39936
	global_load_lds_dwordx4 v[236:237], off
	v_lshl_add_u64 v[236:237], s[26:27], 0, v[138:139]
	s_mov_b32 m0, s43
	s_nop 0
	global_load_lds_dwordx4 v[236:237], off
	s_waitcnt vmcnt(8)
	s_waitcnt lgkmcnt(0)
	s_setprio 1
	s_barrier
	s_waitcnt lgkmcnt(0)
	v_mfma_f32_16x16x32_bf16 v[124:127], v[128:131], v[178:181], v[124:127]
	v_mfma_f32_16x16x32_bf16 v[120:123], v[154:157], v[178:181], v[120:123]
	v_mfma_f32_16x16x32_bf16 v[116:119], v[128:131], v[186:189], v[116:119]
	v_mfma_f32_16x16x32_bf16 v[112:115], v[154:157], v[186:189], v[112:115]
	v_mfma_f32_16x16x32_bf16 v[108:111], v[128:131], v[194:197], v[108:111]
	v_mfma_f32_16x16x32_bf16 v[104:107], v[154:157], v[194:197], v[104:107]
	v_mfma_f32_16x16x32_bf16 v[100:103], v[128:131], v[202:205], v[100:103]
	v_mfma_f32_16x16x32_bf16 v[96:99], v[154:157], v[202:205], v[96:99]
	v_mfma_f32_16x16x32_bf16 v[124:127], v[132:135], v[182:185], v[124:127]
	v_mfma_f32_16x16x32_bf16 v[120:123], v[158:161], v[182:185], v[120:123]
	v_mfma_f32_16x16x32_bf16 v[116:119], v[132:135], v[190:193], v[116:119]
	v_mfma_f32_16x16x32_bf16 v[112:115], v[158:161], v[190:193], v[112:115]
	v_mfma_f32_16x16x32_bf16 v[108:111], v[132:135], v[198:201], v[108:111]
	v_mfma_f32_16x16x32_bf16 v[104:107], v[158:161], v[198:201], v[104:107]
	v_mfma_f32_16x16x32_bf16 v[100:103], v[132:135], v[206:209], v[100:103]
	v_mfma_f32_16x16x32_bf16 v[96:99], v[158:161], v[206:209], v[96:99]
	v_mfma_f32_16x16x32_bf16 v[60:63], v[162:165], v[178:181], v[60:63]
	v_mfma_f32_16x16x32_bf16 v[56:59], v[170:173], v[178:181], v[56:59]
	v_mfma_f32_16x16x32_bf16 v[52:55], v[162:165], v[186:189], v[52:55]
	v_mfma_f32_16x16x32_bf16 v[48:51], v[170:173], v[186:189], v[48:51]
	v_mfma_f32_16x16x32_bf16 v[44:47], v[162:165], v[194:197], v[44:47]
	v_mfma_f32_16x16x32_bf16 v[40:43], v[170:173], v[194:197], v[40:43]
	v_mfma_f32_16x16x32_bf16 v[36:39], v[162:165], v[202:205], v[36:39]
	v_mfma_f32_16x16x32_bf16 v[32:35], v[170:173], v[202:205], v[32:35]
	v_mfma_f32_16x16x32_bf16 v[60:63], v[166:169], v[182:185], v[60:63]
	v_mfma_f32_16x16x32_bf16 v[56:59], v[174:177], v[182:185], v[56:59]
	v_mfma_f32_16x16x32_bf16 v[52:55], v[166:169], v[190:193], v[52:55]
	v_mfma_f32_16x16x32_bf16 v[48:51], v[174:177], v[190:193], v[48:51]
	v_mfma_f32_16x16x32_bf16 v[44:47], v[166:169], v[198:201], v[44:47]
	v_mfma_f32_16x16x32_bf16 v[40:43], v[174:177], v[198:201], v[40:43]
	v_mfma_f32_16x16x32_bf16 v[36:39], v[166:169], v[206:209], v[36:39]
	v_mfma_f32_16x16x32_bf16 v[32:35], v[174:177], v[206:209], v[32:35]
	s_setprio 0
	s_barrier
; #define PG8_STAGE(bufoff, gbase, voff) do { _Pragma("unroll") for (int _i = 0; _i < 2; ++_i) \
;         __builtin_amdgcn_global_load_lds((const unsigned*)((const char*)(gbase) + (voff)[_i]), (PG8_LAS unsigned*)(lds + (bufoff) + ldsw + _i * 8192), 16, 0, 0); } while (0)
; #define PG8_LDA(dst, b, h) do { _Pragma("unroll") for (int m = 0; m < 4; ++m) _Pragma("unroll") for (int k = 0; k < 2; ++k) dst[m][k] = *(const PG8_LAS bf16x8*)(lds + PG8_SA(b, h) + aoff + m * 2048 + k * 1024); } while (0)
; #define PG8_MMA(ai, bj, At, Bt) do { __builtin_amdgcn_s_setprio(1); _Pragma("unroll") for (int m = 0; m < 4; ++m) _Pragma("unroll") for (int n = 0; n < 2; ++n) _Pragma("unroll") for (int k = 0; k < 2; ++k) \
;         acc[ai][bj][m][n] = __builtin_amdgcn_mfma_f32_16x16x32_bf16(Bt[n][k], At[m][k], acc[ai][bj][m][n], 0, 0, 0); __builtin_amdgcn_s_setprio(0); } while (0)
; #define PG8_WAIT_V(n) asm volatile("s_waitcnt vmcnt(" #n ")" ::: "memory")
; #define PG8_WAIT_L(n) asm volatile("s_waitcnt lgkmcnt(" #n ")" ::: "memory")
; #define PG8_BAR __builtin_amdgcn_s_barrier()
; #define PG8_SCHED __builtin_amdgcn_sched_barrier(0)
; template <class Epi, class Sched, bool ALIGN_EPI = false, bool SP2 = false>
; __device__ __forceinline__ void gemm_phase(PG8_LAS unsigned char* lds, const Gemm g, const Sched& S, const Epi& E, int tid_in) {
;     ...
;             PG8_LDA(At, 1, 1); PG8_STAGE(PG8_SB(1, 0), b3, voffB); PG8_STAGE(PG8_SB(1, 1), b3 + hstep, voffB); PG8_STAGE(PG8_SA(1, 0), a3, voffA);
;             PG8_WAIT_V(8); PG8_WAIT_L(0); PG8_BAR; PG8_MMA(1, 0, At, B0); PG8_MMA(1, 1, At, B1); PG8_BAR; PG8_SCHED;
	s_add_i32 s0, s0, s31
	v_lshl_add_u64 v[210:211], v[210:211], 0, vcc
	s_mov_b32 m0, s0
	ds_read_b128 v[178:181], v233 offset:49152
	ds_read_b128 v[182:185], v233 offset:50176
	ds_read_b128 v[186:189], v233 offset:51200
	ds_read_b128 v[190:193], v233 offset:52224
	ds_read_b128 v[194:197], v233 offset:53248
	ds_read_b128 v[198:201], v233 offset:54272
	ds_read_b128 v[202:205], v233 offset:55296
	ds_read_b128 v[206:209], v233 offset:56320
	global_load_lds_dwordx4 v[210:211], off
	v_lshl_add_u64 v[210:211], v[212:213], 0, vcc
	s_add_i32 m0, s0, 0x2000
	s_add_i32 s0, s33, s31
	global_load_lds_dwordx4 v[210:211], off
	v_lshl_add_u64 v[210:211], v[214:215], 0, vcc
	s_mov_b32 m0, s0
	s_nop 0
	global_load_lds_dwordx4 v[210:211], off
	v_lshl_add_u64 v[210:211], v[216:217], 0, vcc
	s_add_i32 m0, s0, 0x2000
	s_nop 0
	global_load_lds_dwordx4 v[210:211], off
	v_lshl_add_u64 v[210:211], v[218:219], 0, vcc
	s_mov_b32 m0, s53
	s_nop 0
	global_load_lds_dwordx4 v[210:211], off
	v_lshl_add_u64 v[210:211], v[234:235], 0, vcc
	s_mov_b32 m0, s54
	s_nop 0
	global_load_lds_dwordx4 v[210:211], off
	s_waitcnt vmcnt(8)
	s_waitcnt lgkmcnt(0)
	s_setprio 1
	s_barrier
	s_waitcnt lgkmcnt(0)
	v_mfma_f32_16x16x32_bf16 v[92:95], v[128:131], v[178:181], v[92:95]
	v_mfma_f32_16x16x32_bf16 v[88:91], v[154:157], v[178:181], v[88:91]
	v_mfma_f32_16x16x32_bf16 v[84:87], v[128:131], v[186:189], v[84:87]
	v_mfma_f32_16x16x32_bf16 v[80:83], v[154:157], v[186:189], v[80:83]
	v_mfma_f32_16x16x32_bf16 v[76:79], v[128:131], v[194:197], v[76:79]
	v_mfma_f32_16x16x32_bf16 v[72:75], v[154:157], v[194:197], v[72:75]
	v_mfma_f32_16x16x32_bf16 v[68:71], v[128:131], v[202:205], v[68:71]
	v_mfma_f32_16x16x32_bf16 v[64:67], v[154:157], v[202:205], v[64:67]
	v_mfma_f32_16x16x32_bf16 v[92:95], v[132:135], v[182:185], v[92:95]
	v_mfma_f32_16x16x32_bf16 v[88:91], v[158:161], v[182:185], v[88:91]
	v_mfma_f32_16x16x32_bf16 v[84:87], v[132:135], v[190:193], v[84:87]
	v_mfma_f32_16x16x32_bf16 v[80:83], v[158:161], v[190:193], v[80:83]
	v_mfma_f32_16x16x32_bf16 v[76:79], v[132:135], v[198:201], v[76:79]
	v_mfma_f32_16x16x32_bf16 v[72:75], v[158:161], v[198:201], v[72:75]
	v_mfma_f32_16x16x32_bf16 v[68:71], v[132:135], v[206:209], v[68:71]
	v_mfma_f32_16x16x32_bf16 v[64:67], v[158:161], v[206:209], v[64:67]
	v_mfma_f32_16x16x32_bf16 v[28:31], v[162:165], v[178:181], v[28:31]
	v_mfma_f32_16x16x32_bf16 v[24:27], v[170:173], v[178:181], v[24:27]
	v_mfma_f32_16x16x32_bf16 v[20:23], v[162:165], v[186:189], v[20:23]
	v_mfma_f32_16x16x32_bf16 v[16:19], v[170:173], v[186:189], v[16:19]
	v_mfma_f32_16x16x32_bf16 v[12:15], v[162:165], v[194:197], v[12:15]
	v_mfma_f32_16x16x32_bf16 v[8:11], v[170:173], v[194:197], v[8:11]
	v_mfma_f32_16x16x32_bf16 v[4:7], v[162:165], v[202:205], v[4:7]
	v_mfma_f32_16x16x32_bf16 v[0:3], v[170:173], v[202:205], v[0:3]
	v_mfma_f32_16x16x32_bf16 v[28:31], v[166:169], v[182:185], v[28:31]
	v_mfma_f32_16x16x32_bf16 v[24:27], v[174:177], v[182:185], v[24:27]
	v_mfma_f32_16x16x32_bf16 v[20:23], v[166:169], v[190:193], v[20:23]
	v_mfma_f32_16x16x32_bf16 v[16:19], v[174:177], v[190:193], v[16:19]
	v_mfma_f32_16x16x32_bf16 v[12:15], v[166:169], v[198:201], v[12:15]
	v_mfma_f32_16x16x32_bf16 v[8:11], v[174:177], v[198:201], v[8:11]
	v_mfma_f32_16x16x32_bf16 v[4:7], v[166:169], v[206:209], v[4:7]
	v_mfma_f32_16x16x32_bf16 v[0:3], v[174:177], v[206:209], v[0:3]
	s_setprio 0
	s_barrier
	s_add_u32 s24, s24, 0x100
	s_addc_u32 s25, s25, 0
	s_add_u32 s68, s68, 0x100
	s_addc_u32 s69, s69, 0
	s_cmp_ge_i32 s1, s17
	s_mov_b32 s0, s1
	s_cbranch_scc0 .LBB0_307
	v_readlane_b32 s70, v253, 53
	s_mov_b64 s[68:69], 0x80
	v_readlane_b32 s71, v253, 54
	s_and_b64 vcc, exec, s[12:13]
	s_cbranch_vccz .LBB0_310

; #define PG8_STAGE(bufoff, gbase, voff) do { _Pragma("unroll") for (int _i = 0; _i < 2; ++_i) \
;         __builtin_amdgcn_global_load_lds((const unsigned*)((const char*)(gbase) + (voff)[_i]), (PG8_LAS unsigned*)(lds + (bufoff) + ldsw + _i * 8192), 16, 0, 0); } while (0)
; #define PG8_LDA(dst, b, h) do { _Pragma("unroll") for (int m = 0; m < 4; ++m) _Pragma("unroll") for (int k = 0; k < 2; ++k) dst[m][k] = *(const PG8_LAS bf16x8*)(lds + PG8_SA(b, h) + aoff + m * 2048 + k * 1024); } while (0)
; #define PG8_LDB(dst, b, h) do { _Pragma("unroll") for (int n = 0; n < 2; ++n) _Pragma("unroll") for (int k = 0; k < 2; ++k) dst[n][k] = *(const PG8_LAS bf16x8*)(lds + PG8_SB(b, h) + boff + n * 2048 + k * 1024); } while (0)
; #define PG8_MMA(ai, bj, At, Bt) do { __builtin_amdgcn_s_setprio(1); _Pragma("unroll") for (int m = 0; m < 4; ++m) _Pragma("unroll") for (int n = 0; n < 2; ++n) _Pragma("unroll") for (int k = 0; k < 2; ++k) \
;         acc[ai][bj][m][n] = __builtin_amdgcn_mfma_f32_16x16x32_bf16(Bt[n][k], At[m][k], acc[ai][bj][m][n], 0, 0, 0); __builtin_amdgcn_s_setprio(0); } while (0)
; #define PG8_WAIT_V(n) asm volatile("s_waitcnt vmcnt(" #n ")" ::: "memory")
; #define PG8_WAIT_L(n) asm volatile("s_waitcnt lgkmcnt(" #n ")" ::: "memory")
; #define PG8_BAR __builtin_amdgcn_s_barrier()
; #define PG8_SCHED __builtin_amdgcn_sched_barrier(0)
; template <class Epi, class Sched, bool ALIGN_EPI = false, bool SP2 = false>
; __device__ __forceinline__ void gemm_phase(PG8_LAS unsigned char* lds, const Gemm g, const Sched& S, const Epi& E, int tid_in) {
;     ...
;         for (int t = 0; t < nt; t += 2) {
;             const bool last = (t == nt - 2);
;             const char* a1 = cA + (size_t)(t + 1) * kstep;
;             const char* a2 = last ? nA : cA + (size_t)(t + 2) * kstep; const char* b2 = last ? nB : cB + (size_t)(t + 2) * kstep;
;             const char* a3 = a2 + kstep; const char* b3 = b2 + kstep;
;             if (last && has_next) S.a_ready(nxt);
;             if constexpr (SP2) {
;             PG8_LDB(B0, 0, 0); PG8_LDB(B1, 0, 1); PG8_SCHED; PG8_LDA(At, 0, 0); PG8_STAGE(PG8_SA(1, 1), a1 + hstep, voffA);
;             PG8_WAIT_V(8); PG8_WAIT_L(0); PG8_BAR; PG8_MMA(0, 0, At, B0); PG8_MMA(0, 1, At, B1); PG8_BAR; PG8_SCHED;
;             PG8_LDA(At, 0, 1); PG8_STAGE(PG8_SB(0, 0), b2, voffB); PG8_STAGE(PG8_SB(0, 1), b2 + hstep, voffB); PG8_STAGE(PG8_SA(0, 0), a2, voffA);
.LBB0_351:
	s_add_u32 s2, s20, 0xfffc0080
	s_addc_u32 s3, s21, -1
	s_add_i32 s33, 0, 0x10000
	s_cmp_eq_u32 s49, 12
	s_cselect_b32 s25, s11, s3
	s_cselect_b32 s24, s44, s2
	s_cselect_b32 s23, s9, s48
	s_cselect_b32 s22, s45, s47
	s_add_i32 s34, 0, 0x14000
	v_add_u32_e32 v60, s33, v164
	v_add_u32_e32 v174, s34, v164
	ds_read_b128 v[48:51], v60
	ds_read_b128 v[52:55], v60 offset:1024
	ds_read_b128 v[56:59], v60 offset:2048
	ds_read_b128 v[60:63], v60 offset:3072
	ds_read_b128 v[158:161], v174
	ds_read_b128 v[166:169], v174 offset:1024
	ds_read_b128 v[170:173], v174 offset:2048
	ds_read_b128 v[174:177], v174 offset:3072
	v_lshl_add_u64 v[210:211], s[20:21], 0, v[154:155]
	s_add_i32 m0, s19, 0xc000
	ds_read_b128 v[178:181], v165
	ds_read_b128 v[182:185], v165 offset:1024
	ds_read_b128 v[186:189], v165 offset:2048
	ds_read_b128 v[190:193], v165 offset:3072
	ds_read_b128 v[194:197], v165 offset:4096
	ds_read_b128 v[198:201], v165 offset:5120
	ds_read_b128 v[202:205], v165 offset:6144
	ds_read_b128 v[206:209], v165 offset:7168
	global_load_lds_dwordx4 v[210:211], off
	v_lshl_add_u64 v[210:211], s[20:21], 0, v[156:157]
	s_add_i32 m0, s19, 0xe000
	s_nop 0
	global_load_lds_dwordx4 v[210:211], off
	s_waitcnt vmcnt(8)
	s_waitcnt lgkmcnt(0)
	s_setprio 1
	s_barrier
	s_waitcnt lgkmcnt(0)
	v_mfma_f32_16x16x32_bf16 v[140:143], v[48:51], v[178:181], v[140:143]
	v_mfma_f32_16x16x32_bf16 v[136:139], v[56:59], v[178:181], v[136:139]
	v_mfma_f32_16x16x32_bf16 v[124:127], v[48:51], v[186:189], v[124:127]
	v_mfma_f32_16x16x32_bf16 v[120:123], v[56:59], v[186:189], v[120:123]
	v_mfma_f32_16x16x32_bf16 v[108:111], v[48:51], v[194:197], v[108:111]
	v_mfma_f32_16x16x32_bf16 v[104:107], v[56:59], v[194:197], v[104:107]
	v_mfma_f32_16x16x32_bf16 v[92:95], v[48:51], v[202:205], v[92:95]
	v_mfma_f32_16x16x32_bf16 v[88:91], v[56:59], v[202:205], v[88:91]
	v_mfma_f32_16x16x32_bf16 v[140:143], v[52:55], v[182:185], v[140:143]
	v_mfma_f32_16x16x32_bf16 v[136:139], v[60:63], v[182:185], v[136:139]
	v_mfma_f32_16x16x32_bf16 v[124:127], v[52:55], v[190:193], v[124:127]
	v_mfma_f32_16x16x32_bf16 v[120:123], v[60:63], v[190:193], v[120:123]
	v_mfma_f32_16x16x32_bf16 v[108:111], v[52:55], v[198:201], v[108:111]
	v_mfma_f32_16x16x32_bf16 v[104:107], v[60:63], v[198:201], v[104:107]
	v_mfma_f32_16x16x32_bf16 v[92:95], v[52:55], v[206:209], v[92:95]
	v_mfma_f32_16x16x32_bf16 v[88:91], v[60:63], v[206:209], v[88:91]
	v_mfma_f32_16x16x32_bf16 v[132:135], v[158:161], v[178:181], v[132:135]
	v_mfma_f32_16x16x32_bf16 v[128:131], v[170:173], v[178:181], v[128:131]
	v_mfma_f32_16x16x32_bf16 v[116:119], v[158:161], v[186:189], v[116:119]
	v_mfma_f32_16x16x32_bf16 v[112:115], v[170:173], v[186:189], v[112:115]
	v_mfma_f32_16x16x32_bf16 v[100:103], v[158:161], v[194:197], v[100:103]
	v_mfma_f32_16x16x32_bf16 v[96:99], v[170:173], v[194:197], v[96:99]
	v_mfma_f32_16x16x32_bf16 v[84:87], v[158:161], v[202:205], v[84:87]
	v_mfma_f32_16x16x32_bf16 v[80:83], v[170:173], v[202:205], v[80:83]
	v_mfma_f32_16x16x32_bf16 v[132:135], v[166:169], v[182:185], v[132:135]
	v_mfma_f32_16x16x32_bf16 v[128:131], v[174:177], v[182:185], v[128:131]
	v_mfma_f32_16x16x32_bf16 v[116:119], v[166:169], v[190:193], v[116:119]
	v_mfma_f32_16x16x32_bf16 v[112:115], v[174:177], v[190:193], v[112:115]
	v_mfma_f32_16x16x32_bf16 v[100:103], v[166:169], v[198:201], v[100:103]
	v_mfma_f32_16x16x32_bf16 v[96:99], v[174:177], v[198:201], v[96:99]
	v_mfma_f32_16x16x32_bf16 v[84:87], v[166:169], v[206:209], v[84:87]
	v_mfma_f32_16x16x32_bf16 v[80:83], v[174:177], v[206:209], v[80:83]
	s_setprio 0
	s_barrier
	s_add_i32 s2, s33, s35
	v_lshl_add_u64 v[210:211], s[22:23], 0, v[144:145]
	s_mov_b32 m0, s2
	ds_read_b128 v[178:181], v165 offset:16384
	ds_read_b128 v[182:185], v165 offset:17408
	ds_read_b128 v[186:189], v165 offset:18432
	ds_read_b128 v[190:193], v165 offset:19456
	ds_read_b128 v[194:197], v165 offset:20480
	ds_read_b128 v[198:201], v165 offset:21504
	ds_read_b128 v[202:205], v165 offset:22528
	ds_read_b128 v[206:209], v165 offset:23552
	global_load_lds_dwordx4 v[210:211], off
	s_add_i32 m0, s2, 0x2000
	s_add_u32 s2, s22, 0x40000
	v_lshl_add_u64 v[212:213], s[22:23], 0, v[148:149]
	s_addc_u32 s3, s23, 0
	s_add_i32 s33, s34, s35
	global_load_lds_dwordx4 v[212:213], off
	v_lshl_add_u64 v[214:215], s[2:3], 0, v[144:145]
	s_mov_b32 m0, s33
	v_lshl_add_u64 v[216:217], s[24:25], 0, v[150:151]
	global_load_lds_dwordx4 v[214:215], off
	v_lshl_add_u64 v[214:215], s[2:3], 0, v[148:149]
	s_add_i32 m0, s33, 0x2000
	s_nop 0
	global_load_lds_dwordx4 v[214:215], off
	v_lshl_add_u64 v[214:215], s[24:25], 0, v[152:153]
	s_mov_b32 m0, s19
	s_nop 0
	global_load_lds_dwordx4 v[214:215], off
	s_mov_b32 m0, s36
	s_nop 0
	global_load_lds_dwordx4 v[216:217], off
	s_waitcnt vmcnt(8)
	s_waitcnt lgkmcnt(0)
	s_setprio 1
	s_barrier
; #define PG8_STAGE(bufoff, gbase, voff) do { _Pragma("unroll") for (int _i = 0; _i < 2; ++_i) \
;         __builtin_amdgcn_global_load_lds((const unsigned*)((const char*)(gbase) + (voff)[_i]), (PG8_LAS unsigned*)(lds + (bufoff) + ldsw + _i * 8192), 16, 0, 0); } while (0)
; #define PG8_LDA(dst, b, h) do { _Pragma("unroll") for (int m = 0; m < 4; ++m) _Pragma("unroll") for (int k = 0; k < 2; ++k) dst[m][k] = *(const PG8_LAS bf16x8*)(lds + PG8_SA(b, h) + aoff + m * 2048 + k * 1024); } while (0)
; #define PG8_LDB(dst, b, h) do { _Pragma("unroll") for (int n = 0; n < 2; ++n) _Pragma("unroll") for (int k = 0; k < 2; ++k) dst[n][k] = *(const PG8_LAS bf16x8*)(lds + PG8_SB(b, h) + boff + n * 2048 + k * 1024); } while (0)
; #define PG8_MMA(ai, bj, At, Bt) do { __builtin_amdgcn_s_setprio(1); _Pragma("unroll") for (int m = 0; m < 4; ++m) _Pragma("unroll") for (int n = 0; n < 2; ++n) _Pragma("unroll") for (int k = 0; k < 2; ++k) \
;         acc[ai][bj][m][n] = __builtin_amdgcn_mfma_f32_16x16x32_bf16(Bt[n][k], At[m][k], acc[ai][bj][m][n], 0, 0, 0); __builtin_amdgcn_s_setprio(0); } while (0)
; #define PG8_WAIT_V(n) asm volatile("s_waitcnt vmcnt(" #n ")" ::: "memory")
; #define PG8_WAIT_L(n) asm volatile("s_waitcnt lgkmcnt(" #n ")" ::: "memory")
; #define PG8_BAR __builtin_amdgcn_s_barrier()
; #define PG8_SCHED __builtin_amdgcn_sched_barrier(0)
; template <class Epi, class Sched, bool ALIGN_EPI = false, bool SP2 = false>
; __device__ __forceinline__ void gemm_phase(PG8_LAS unsigned char* lds, const Gemm g, const Sched& S, const Epi& E, int tid_in) {
;     ...
;             PG8_LDA(At, 0, 1); PG8_STAGE(PG8_SB(0, 0), b2, voffB); PG8_STAGE(PG8_SB(0, 1), b2 + hstep, voffB); PG8_STAGE(PG8_SA(0, 0), a2, voffA);
;             PG8_WAIT_V(8); PG8_WAIT_L(0); PG8_BAR; PG8_MMA(1, 0, At, B0); PG8_MMA(1, 1, At, B1); PG8_BAR; PG8_SCHED;
;             PG8_LDB(B0, 1, 0); PG8_LDB(B1, 1, 1); PG8_SCHED; PG8_LDA(At, 1, 0); PG8_STAGE(PG8_SA(0, 1), a2 + hstep, voffA);
;             PG8_WAIT_V(8); PG8_WAIT_L(0); PG8_BAR; PG8_MMA(0, 0, At, B0); PG8_MMA(0, 1, At, B1); PG8_BAR; PG8_SCHED;
	s_waitcnt lgkmcnt(0)
	v_mfma_f32_16x16x32_bf16 v[76:79], v[48:51], v[178:181], v[76:79]
	v_mfma_f32_16x16x32_bf16 v[72:75], v[56:59], v[178:181], v[72:75]
	v_mfma_f32_16x16x32_bf16 v[44:47], v[48:51], v[186:189], v[44:47]
	v_mfma_f32_16x16x32_bf16 v[40:43], v[56:59], v[186:189], v[40:43]
	v_mfma_f32_16x16x32_bf16 v[28:31], v[48:51], v[194:197], v[28:31]
	v_mfma_f32_16x16x32_bf16 v[24:27], v[56:59], v[194:197], v[24:27]
	v_mfma_f32_16x16x32_bf16 v[12:15], v[48:51], v[202:205], v[12:15]
	v_mfma_f32_16x16x32_bf16 v[8:11], v[56:59], v[202:205], v[8:11]
	v_mfma_f32_16x16x32_bf16 v[76:79], v[52:55], v[182:185], v[76:79]
	v_mfma_f32_16x16x32_bf16 v[72:75], v[60:63], v[182:185], v[72:75]
	v_mfma_f32_16x16x32_bf16 v[44:47], v[52:55], v[190:193], v[44:47]
	v_mfma_f32_16x16x32_bf16 v[40:43], v[60:63], v[190:193], v[40:43]
	v_mfma_f32_16x16x32_bf16 v[28:31], v[52:55], v[198:201], v[28:31]
	v_mfma_f32_16x16x32_bf16 v[24:27], v[60:63], v[198:201], v[24:27]
	v_mfma_f32_16x16x32_bf16 v[12:15], v[52:55], v[206:209], v[12:15]
	v_mfma_f32_16x16x32_bf16 v[8:11], v[60:63], v[206:209], v[8:11]
	v_mfma_f32_16x16x32_bf16 v[36:39], v[158:161], v[186:189], v[36:39]
	v_mfma_f32_16x16x32_bf16 v[32:35], v[170:173], v[186:189], v[32:35]
	v_mfma_f32_16x16x32_bf16 v[20:23], v[158:161], v[194:197], v[20:23]
	v_mfma_f32_16x16x32_bf16 v[16:19], v[170:173], v[194:197], v[16:19]
	v_mfma_f32_16x16x32_bf16 v[4:7], v[158:161], v[202:205], v[4:7]
	v_mfma_f32_16x16x32_bf16 v[0:3], v[170:173], v[202:205], v[0:3]
	v_mfma_f32_16x16x32_bf16 v[48:51], v[158:161], v[178:181], v[68:71]
	v_mfma_f32_16x16x32_bf16 v[52:55], v[170:173], v[178:181], v[64:67]
	v_mfma_f32_16x16x32_bf16 v[36:39], v[166:169], v[190:193], v[36:39]
	v_mfma_f32_16x16x32_bf16 v[32:35], v[174:177], v[190:193], v[32:35]
	v_mfma_f32_16x16x32_bf16 v[20:23], v[166:169], v[198:201], v[20:23]
	v_mfma_f32_16x16x32_bf16 v[16:19], v[174:177], v[198:201], v[16:19]
	v_mfma_f32_16x16x32_bf16 v[4:7], v[166:169], v[206:209], v[4:7]
	v_mfma_f32_16x16x32_bf16 v[0:3], v[174:177], v[206:209], v[0:3]
	v_mfma_f32_16x16x32_bf16 v[48:51], v[166:169], v[182:185], v[48:51]
	v_mfma_f32_16x16x32_bf16 v[52:55], v[174:177], v[182:185], v[52:55]
	s_setprio 0
	s_barrier
	s_add_i32 s33, 0, 0x18000
	s_add_i32 s34, 0, 0x1c000
	v_add_u32_e32 v68, s33, v164
	v_add_u32_e32 v174, s34, v164
	ds_read_b128 v[56:59], v68
	ds_read_b128 v[60:63], v68 offset:1024
	ds_read_b128 v[64:67], v68 offset:2048
	ds_read_b128 v[68:71], v68 offset:3072
	ds_read_b128 v[158:161], v174
	ds_read_b128 v[166:169], v174 offset:1024
	ds_read_b128 v[170:173], v174 offset:2048
	ds_read_b128 v[174:177], v174 offset:3072
	s_add_u32 s2, s24, 0x40000
	s_addc_u32 s3, s25, 0
	s_mov_b32 m0, s37
	v_lshl_add_u64 v[218:219], s[2:3], 0, v[152:153]
	ds_read_b128 v[178:181], v165 offset:32768
	ds_read_b128 v[182:185], v165 offset:33792
	ds_read_b128 v[186:189], v165 offset:34816
	ds_read_b128 v[190:193], v165 offset:35840
	ds_read_b128 v[194:197], v165 offset:36864
	ds_read_b128 v[198:201], v165 offset:37888
	ds_read_b128 v[202:205], v165 offset:38912
	ds_read_b128 v[206:209], v165 offset:39936
	global_load_lds_dwordx4 v[218:219], off
	v_lshl_add_u64 v[218:219], s[2:3], 0, v[150:151]
	s_mov_b32 m0, s38
	s_nop 0
	global_load_lds_dwordx4 v[218:219], off
	s_waitcnt vmcnt(8)
	s_waitcnt lgkmcnt(0)
	s_setprio 1
	s_barrier
	s_waitcnt lgkmcnt(0)
	v_mfma_f32_16x16x32_bf16 v[140:143], v[56:59], v[178:181], v[140:143]
	v_mfma_f32_16x16x32_bf16 v[136:139], v[64:67], v[178:181], v[136:139]
	v_mfma_f32_16x16x32_bf16 v[124:127], v[56:59], v[186:189], v[124:127]
	v_mfma_f32_16x16x32_bf16 v[120:123], v[64:67], v[186:189], v[120:123]
	v_mfma_f32_16x16x32_bf16 v[108:111], v[56:59], v[194:197], v[108:111]
	v_mfma_f32_16x16x32_bf16 v[104:107], v[64:67], v[194:197], v[104:107]
	v_mfma_f32_16x16x32_bf16 v[92:95], v[56:59], v[202:205], v[92:95]
	v_mfma_f32_16x16x32_bf16 v[88:91], v[64:67], v[202:205], v[88:91]
	v_mfma_f32_16x16x32_bf16 v[140:143], v[60:63], v[182:185], v[140:143]
	v_mfma_f32_16x16x32_bf16 v[136:139], v[68:71], v[182:185], v[136:139]
	v_mfma_f32_16x16x32_bf16 v[124:127], v[60:63], v[190:193], v[124:127]
	v_mfma_f32_16x16x32_bf16 v[120:123], v[68:71], v[190:193], v[120:123]
	v_mfma_f32_16x16x32_bf16 v[108:111], v[60:63], v[198:201], v[108:111]
	v_mfma_f32_16x16x32_bf16 v[104:107], v[68:71], v[198:201], v[104:107]
	v_mfma_f32_16x16x32_bf16 v[92:95], v[60:63], v[206:209], v[92:95]
	v_mfma_f32_16x16x32_bf16 v[88:91], v[68:71], v[206:209], v[88:91]
	v_mfma_f32_16x16x32_bf16 v[132:135], v[158:161], v[178:181], v[132:135]
	v_mfma_f32_16x16x32_bf16 v[128:131], v[170:173], v[178:181], v[128:131]
	v_mfma_f32_16x16x32_bf16 v[116:119], v[158:161], v[186:189], v[116:119]
	v_mfma_f32_16x16x32_bf16 v[112:115], v[170:173], v[186:189], v[112:115]
	v_mfma_f32_16x16x32_bf16 v[100:103], v[158:161], v[194:197], v[100:103]
	v_mfma_f32_16x16x32_bf16 v[96:99], v[170:173], v[194:197], v[96:99]
	v_mfma_f32_16x16x32_bf16 v[84:87], v[158:161], v[202:205], v[84:87]
	v_mfma_f32_16x16x32_bf16 v[80:83], v[170:173], v[202:205], v[80:83]
	v_mfma_f32_16x16x32_bf16 v[132:135], v[166:169], v[182:185], v[132:135]
	v_mfma_f32_16x16x32_bf16 v[128:131], v[174:177], v[182:185], v[128:131]
	v_mfma_f32_16x16x32_bf16 v[116:119], v[166:169], v[190:193], v[116:119]
	v_mfma_f32_16x16x32_bf16 v[112:115], v[174:177], v[190:193], v[112:115]
	v_mfma_f32_16x16x32_bf16 v[100:103], v[166:169], v[198:201], v[100:103]
	v_mfma_f32_16x16x32_bf16 v[96:99], v[174:177], v[198:201], v[96:99]
	v_mfma_f32_16x16x32_bf16 v[84:87], v[166:169], v[206:209], v[84:87]
	v_mfma_f32_16x16x32_bf16 v[80:83], v[174:177], v[206:209], v[80:83]
	s_setprio 0
	s_barrier
; #define PG8_STAGE(bufoff, gbase, voff) do { _Pragma("unroll") for (int _i = 0; _i < 2; ++_i) \
;         __builtin_amdgcn_global_load_lds((const unsigned*)((const char*)(gbase) + (voff)[_i]), (PG8_LAS unsigned*)(lds + (bufoff) + ldsw + _i * 8192), 16, 0, 0); } while (0)
; #define PG8_LDA(dst, b, h) do { _Pragma("unroll") for (int m = 0; m < 4; ++m) _Pragma("unroll") for (int k = 0; k < 2; ++k) dst[m][k] = *(const PG8_LAS bf16x8*)(lds + PG8_SA(b, h) + aoff + m * 2048 + k * 1024); } while (0)
; #define PG8_MMA(ai, bj, At, Bt) do { __builtin_amdgcn_s_setprio(1); _Pragma("unroll") for (int m = 0; m < 4; ++m) _Pragma("unroll") for (int n = 0; n < 2; ++n) _Pragma("unroll") for (int k = 0; k < 2; ++k) \
;         acc[ai][bj][m][n] = __builtin_amdgcn_mfma_f32_16x16x32_bf16(Bt[n][k], At[m][k], acc[ai][bj][m][n], 0, 0, 0); __builtin_amdgcn_s_setprio(0); } while (0)
; #define PG8_WAIT_V(n) asm volatile("s_waitcnt vmcnt(" #n ")" ::: "memory")
; #define PG8_WAIT_L(n) asm volatile("s_waitcnt lgkmcnt(" #n ")" ::: "memory")
; #define PG8_BAR __builtin_amdgcn_s_barrier()
; #define PG8_SCHED __builtin_amdgcn_sched_barrier(0)
; template <class Epi, class Sched, bool ALIGN_EPI = false, bool SP2 = false>
; __device__ __forceinline__ void gemm_phase(PG8_LAS unsigned char* lds, const Gemm g, const Sched& S, const Epi& E, int tid_in) {
;     ...
;             PG8_LDA(At, 1, 1); PG8_STAGE(PG8_SB(1, 0), b3, voffB); PG8_STAGE(PG8_SB(1, 1), b3 + hstep, voffB); PG8_STAGE(PG8_SA(1, 0), a3, voffA);
;             PG8_WAIT_V(8); PG8_WAIT_L(0); PG8_BAR; PG8_MMA(1, 0, At, B0); PG8_MMA(1, 1, At, B1); PG8_BAR; PG8_SCHED;
	s_add_i32 s2, s33, s35
	v_lshl_add_u64 v[210:211], v[210:211], 0, s[68:69]
	s_mov_b32 m0, s2
	ds_read_b128 v[178:181], v165 offset:49152
	ds_read_b128 v[182:185], v165 offset:50176
	ds_read_b128 v[186:189], v165 offset:51200
	ds_read_b128 v[190:193], v165 offset:52224
	ds_read_b128 v[194:197], v165 offset:53248
	ds_read_b128 v[198:201], v165 offset:54272
	ds_read_b128 v[202:205], v165 offset:55296
	ds_read_b128 v[206:209], v165 offset:56320
	global_load_lds_dwordx4 v[210:211], off
	s_add_i32 m0, s2, 0x2000
	s_add_u32 s2, s22, 0x40080
	v_lshl_add_u64 v[210:211], v[212:213], 0, s[68:69]
	s_addc_u32 s3, s23, 0
	s_add_i32 s22, s34, s35
	global_load_lds_dwordx4 v[210:211], off
	v_lshl_add_u64 v[210:211], s[2:3], 0, v[144:145]
	s_mov_b32 m0, s22
	s_nop 0
	global_load_lds_dwordx4 v[210:211], off
	v_lshl_add_u64 v[210:211], s[2:3], 0, v[148:149]
	s_add_i32 m0, s22, 0x2000
	s_nop 0
	global_load_lds_dwordx4 v[210:211], off
	v_lshl_add_u64 v[210:211], v[214:215], 0, s[68:69]
	s_mov_b32 m0, s41
	s_nop 0
	global_load_lds_dwordx4 v[210:211], off
	v_lshl_add_u64 v[210:211], v[216:217], 0, s[68:69]
	s_mov_b32 m0, s42
	s_nop 0
	global_load_lds_dwordx4 v[210:211], off
	s_waitcnt vmcnt(8)
	s_waitcnt lgkmcnt(0)
	s_setprio 1
	s_barrier
	s_waitcnt lgkmcnt(0)
	v_mfma_f32_16x16x32_bf16 v[76:79], v[56:59], v[178:181], v[76:79]
	v_mfma_f32_16x16x32_bf16 v[72:75], v[64:67], v[178:181], v[72:75]
	v_mfma_f32_16x16x32_bf16 v[44:47], v[56:59], v[186:189], v[44:47]
	v_mfma_f32_16x16x32_bf16 v[40:43], v[64:67], v[186:189], v[40:43]
	v_mfma_f32_16x16x32_bf16 v[28:31], v[56:59], v[194:197], v[28:31]
	v_mfma_f32_16x16x32_bf16 v[24:27], v[64:67], v[194:197], v[24:27]
	v_mfma_f32_16x16x32_bf16 v[12:15], v[56:59], v[202:205], v[12:15]
	v_mfma_f32_16x16x32_bf16 v[8:11], v[64:67], v[202:205], v[8:11]
	v_mfma_f32_16x16x32_bf16 v[76:79], v[60:63], v[182:185], v[76:79]
	v_mfma_f32_16x16x32_bf16 v[72:75], v[68:71], v[182:185], v[72:75]
	v_mfma_f32_16x16x32_bf16 v[44:47], v[60:63], v[190:193], v[44:47]
	v_mfma_f32_16x16x32_bf16 v[40:43], v[68:71], v[190:193], v[40:43]
	v_mfma_f32_16x16x32_bf16 v[28:31], v[60:63], v[198:201], v[28:31]
	v_mfma_f32_16x16x32_bf16 v[24:27], v[68:71], v[198:201], v[24:27]
	v_mfma_f32_16x16x32_bf16 v[12:15], v[60:63], v[206:209], v[12:15]
	v_mfma_f32_16x16x32_bf16 v[8:11], v[68:71], v[206:209], v[8:11]
	v_mfma_f32_16x16x32_bf16 v[48:51], v[158:161], v[178:181], v[48:51]
	v_mfma_f32_16x16x32_bf16 v[68:71], v[166:169], v[182:185], v[48:51]
	v_mfma_f32_16x16x32_bf16 v[48:51], v[170:173], v[178:181], v[52:55]
	v_mfma_f32_16x16x32_bf16 v[36:39], v[158:161], v[186:189], v[36:39]
	v_mfma_f32_16x16x32_bf16 v[32:35], v[170:173], v[186:189], v[32:35]
	v_mfma_f32_16x16x32_bf16 v[20:23], v[158:161], v[194:197], v[20:23]
	v_mfma_f32_16x16x32_bf16 v[16:19], v[170:173], v[194:197], v[16:19]
	v_mfma_f32_16x16x32_bf16 v[4:7], v[158:161], v[202:205], v[4:7]
	v_mfma_f32_16x16x32_bf16 v[0:3], v[170:173], v[202:205], v[0:3]
	v_mfma_f32_16x16x32_bf16 v[64:67], v[174:177], v[182:185], v[48:51]
	v_mfma_f32_16x16x32_bf16 v[36:39], v[166:169], v[190:193], v[36:39]
	v_mfma_f32_16x16x32_bf16 v[32:35], v[174:177], v[190:193], v[32:35]
	v_mfma_f32_16x16x32_bf16 v[20:23], v[166:169], v[198:201], v[20:23]
	v_mfma_f32_16x16x32_bf16 v[16:19], v[174:177], v[198:201], v[16:19]
	v_mfma_f32_16x16x32_bf16 v[4:7], v[166:169], v[206:209], v[4:7]
	v_mfma_f32_16x16x32_bf16 v[0:3], v[174:177], v[206:209], v[0:3]
	s_setprio 0
	s_barrier
	s_add_i32 s49, s49, 2
	s_add_u32 s20, s20, 0x100
	s_addc_u32 s21, s21, 0
	s_add_u32 s47, s47, 0x100
	s_addc_u32 s48, s48, 0
	s_cmp_gt_u32 s49, 13
	s_cbranch_scc0 .LBB0_351
	s_and_b64 vcc, exec, s[6:7]
	s_cbranch_vccz .LBB0_354
	s_barrier
